# redundant phase-end s_barrier removed at three GEMM phase ends (the seam re-waits and re-barriers), counted lgkmcnt waits for the hoisted rinv reads in the SwiGLU epilogue
# speedup vs baseline: 1.0070x; 1.0070x over previous
; __device__ __forceinline__ unsigned cvt_pk_bf16(float lo, float hi) { unsigned r; asm volatile("v_cvt_pk_bf16_f32 %0, %1, %2" : "=v"(r) : "v"(lo), "v"(hi)); return r; }
;     __device__ __forceinline__ void operator()(const f32x4 (&acc)[2][2][4][2], const Unit& u, int wr, int wc, int fr, int fq) const {
;         const int row0 = u.pm * BM + u.roff + wr * 64 + fr, col0 = u.pn * HALF + wc * 32 + 8 * fq;
; #pragma unroll
;         for (int ai = 0; ai < NAI; ++ai)
; #pragma unroll
;             for (int m = 0; m < 4; ++m) {
;                 const int row = row0 + ai * HALF + m * 16; const float ri = tab[u.par * 256 + ai * HALF + wr * 64 + m * 16 + fr];
;                 const f32x4 g0 = acc[ai][0][m][0] * ri, g1 = acc[ai][0][m][1] * ri, u0 = acc[ai][1][m][0] * ri, u1 = acc[ai][1][m][1] * ri;
;                 u32x4 w;
;                 w.x = pg8::cvt_pk_bf16(silu_mul(g0[0], u0[0]), silu_mul(g0[1], u0[1])); w.y = pg8::cvt_pk_bf16(silu_mul(g0[2], u0[2]), silu_mul(g0[3], u0[3]));
;                 w.z = pg8::cvt_pk_bf16(silu_mul(g1[0], u1[0]), silu_mul(g1[1], u1[1])); w.w = pg8::cvt_pk_bf16(silu_mul(g1[2], u1[2]), silu_mul(g1[3], u1[3]));
;                 *(u32x4*)(O + (size_t)row * DFF + col0) = w;
;                 if (m & 1) asm volatile("" ::: "memory");
;             }
.LBB0_185:
	v_lshl_add_u32 v147, s55, 10, v145
	ds_read_b32 v202, v147
	ds_read_b32 v203, v147 offset:64
	ds_read_b32 v204, v147 offset:128
	ds_read_b32 v205, v147 offset:192
	ds_read_b32 v206, v147 offset:512
	ds_read_b32 v207, v147 offset:576
	ds_read_b32 v208, v147 offset:640
	ds_read_b32 v209, v147 offset:704
	v_readlane_b32 s18, v254, 11
	v_lshl_or_b32 v140, s56, 7, v144
	v_readlane_b32 s19, v254, 12
	v_lshl_add_u32 v148, s57, 8, v142
	v_ashrrev_i32_e32 v141, 31, v140
	v_lshlrev_b64 v[210:211], 1, v[140:141]
	s_nop 1
	v_mov_b64_e32 v[212:213], s[18:19]
	s_waitcnt lgkmcnt(7)
	v_mul_f32_e32 v214, 0xbfb8aa3b, v202
	v_mul_f32_e32 v220, v202, v202
	v_mul_f32_e32 v216, v126, v214
	v_mul_f32_e32 v217, v127, v214
	v_exp_f32_e32 v216, v216
	v_exp_f32_e32 v217, v217
	v_pk_mul_f32 v[218:219], v[126:127], v[118:119]
	v_pk_add_f32 v[216:217], v[216:217], 1.0 op_sel_hi:[1,0]
	v_pk_mul_f32 v[218:219], v[218:219], v[220:221] op_sel_hi:[1,0]
	v_rcp_f32_e32 v216, v216
	v_rcp_f32_e32 v217, v217
	s_nop 0
	v_pk_mul_f32 v[218:219], v[218:219], v[216:217]
	v_cvt_pk_bf16_f32 v226, v218, v219
	v_mul_f32_e32 v216, v128, v214
	v_mul_f32_e32 v217, v129, v214
	v_exp_f32_e32 v216, v216
	v_exp_f32_e32 v217, v217
	v_pk_mul_f32 v[218:219], v[128:129], v[120:121]
	v_pk_add_f32 v[216:217], v[216:217], 1.0 op_sel_hi:[1,0]
	v_pk_mul_f32 v[218:219], v[218:219], v[220:221] op_sel_hi:[1,0]
	v_rcp_f32_e32 v216, v216
	v_rcp_f32_e32 v217, v217
	s_nop 0
	v_pk_mul_f32 v[218:219], v[218:219], v[216:217]
	v_cvt_pk_bf16_f32 v227, v218, v219
	v_mul_f32_e32 v216, v122, v214
	v_mul_f32_e32 v217, v123, v214
	v_exp_f32_e32 v216, v216
	v_exp_f32_e32 v217, v217
	v_pk_mul_f32 v[218:219], v[122:123], v[114:115]
	v_pk_add_f32 v[216:217], v[216:217], 1.0 op_sel_hi:[1,0]
	v_pk_mul_f32 v[218:219], v[218:219], v[220:221] op_sel_hi:[1,0]
	v_rcp_f32_e32 v216, v216
	v_rcp_f32_e32 v217, v217
	s_nop 0
	v_pk_mul_f32 v[218:219], v[218:219], v[216:217]
	v_cvt_pk_bf16_f32 v228, v218, v219
	v_mul_f32_e32 v216, v124, v214
	v_mul_f32_e32 v217, v125, v214
	v_exp_f32_e32 v216, v216
	v_exp_f32_e32 v217, v217
	v_pk_mul_f32 v[218:219], v[124:125], v[116:117]
	v_pk_add_f32 v[216:217], v[216:217], 1.0 op_sel_hi:[1,0]
	v_pk_mul_f32 v[218:219], v[218:219], v[220:221] op_sel_hi:[1,0]
	v_rcp_f32_e32 v216, v216
	v_rcp_f32_e32 v217, v217
	s_nop 0
	v_pk_mul_f32 v[218:219], v[218:219], v[216:217]
	v_cvt_pk_bf16_f32 v229, v218, v219
	v_mov_b32_e32 v222, v148
	v_mad_i64_i32 v[224:225], s[18:19], v222, s41, v[212:213]
	v_lshl_add_u64 v[224:225], v[224:225], 0, v[210:211]
	global_store_dwordx4 v[224:225], v[226:229], off
	s_waitcnt lgkmcnt(6)
	v_mul_f32_e32 v214, 0xbfb8aa3b, v203
	v_mul_f32_e32 v220, v203, v203
	v_mul_f32_e32 v216, v110, v214
	v_mul_f32_e32 v217, v111, v214
	v_exp_f32_e32 v216, v216
	v_exp_f32_e32 v217, v217
	v_pk_mul_f32 v[218:219], v[110:111], v[102:103]
	v_pk_add_f32 v[216:217], v[216:217], 1.0 op_sel_hi:[1,0]
	v_pk_mul_f32 v[218:219], v[218:219], v[220:221] op_sel_hi:[1,0]
	v_rcp_f32_e32 v216, v216
	v_rcp_f32_e32 v217, v217
	s_nop 0
	v_pk_mul_f32 v[218:219], v[218:219], v[216:217]
	v_cvt_pk_bf16_f32 v226, v218, v219
	v_mul_f32_e32 v216, v112, v214
	v_mul_f32_e32 v217, v113, v214
	v_exp_f32_e32 v216, v216
	v_exp_f32_e32 v217, v217
	v_pk_mul_f32 v[218:219], v[112:113], v[104:105]
	v_pk_add_f32 v[216:217], v[216:217], 1.0 op_sel_hi:[1,0]
	v_pk_mul_f32 v[218:219], v[218:219], v[220:221] op_sel_hi:[1,0]
	v_rcp_f32_e32 v216, v216
	v_rcp_f32_e32 v217, v217
	s_nop 0
	v_pk_mul_f32 v[218:219], v[218:219], v[216:217]
	v_cvt_pk_bf16_f32 v227, v218, v219
	v_mul_f32_e32 v216, v106, v214
	v_mul_f32_e32 v217, v107, v214
	v_exp_f32_e32 v216, v216
	v_exp_f32_e32 v217, v217
	v_pk_mul_f32 v[218:219], v[106:107], v[98:99]
	v_pk_add_f32 v[216:217], v[216:217], 1.0 op_sel_hi:[1,0]
	v_pk_mul_f32 v[218:219], v[218:219], v[220:221] op_sel_hi:[1,0]
	v_rcp_f32_e32 v216, v216
	v_rcp_f32_e32 v217, v217
	s_nop 0
	v_pk_mul_f32 v[218:219], v[218:219], v[216:217]
	v_cvt_pk_bf16_f32 v228, v218, v219
	v_mul_f32_e32 v216, v108, v214
	v_mul_f32_e32 v217, v109, v214
	v_exp_f32_e32 v216, v216
	v_exp_f32_e32 v217, v217
	v_pk_mul_f32 v[218:219], v[108:109], v[100:101]
	v_pk_add_f32 v[216:217], v[216:217], 1.0 op_sel_hi:[1,0]
	v_pk_mul_f32 v[218:219], v[218:219], v[220:221] op_sel_hi:[1,0]
	v_rcp_f32_e32 v216, v216
	v_rcp_f32_e32 v217, v217
	s_nop 0
	v_pk_mul_f32 v[218:219], v[218:219], v[216:217]
	v_cvt_pk_bf16_f32 v229, v218, v219
	v_add_u32_e32 v222, 16, v148
	v_mad_i64_i32 v[224:225], s[18:19], v222, s41, v[212:213]
	v_lshl_add_u64 v[224:225], v[224:225], 0, v[210:211]
	global_store_dwordx4 v[224:225], v[226:229], off
	s_waitcnt lgkmcnt(5)
	v_mul_f32_e32 v214, 0xbfb8aa3b, v204
	v_mul_f32_e32 v220, v204, v204
	v_mul_f32_e32 v216, v94, v214
	v_mul_f32_e32 v217, v95, v214
	v_exp_f32_e32 v216, v216
	v_exp_f32_e32 v217, v217
	v_pk_mul_f32 v[218:219], v[94:95], v[86:87]
	v_pk_add_f32 v[216:217], v[216:217], 1.0 op_sel_hi:[1,0]
	v_pk_mul_f32 v[218:219], v[218:219], v[220:221] op_sel_hi:[1,0]
	v_rcp_f32_e32 v216, v216
	v_rcp_f32_e32 v217, v217
	s_nop 0
	v_pk_mul_f32 v[218:219], v[218:219], v[216:217]
	v_cvt_pk_bf16_f32 v226, v218, v219
	v_mul_f32_e32 v216, v96, v214
	v_mul_f32_e32 v217, v97, v214
	v_exp_f32_e32 v216, v216
	v_exp_f32_e32 v217, v217
	v_pk_mul_f32 v[218:219], v[96:97], v[88:89]
	v_pk_add_f32 v[216:217], v[216:217], 1.0 op_sel_hi:[1,0]
	v_pk_mul_f32 v[218:219], v[218:219], v[220:221] op_sel_hi:[1,0]
	v_rcp_f32_e32 v216, v216
	v_rcp_f32_e32 v217, v217
	s_nop 0
	v_pk_mul_f32 v[218:219], v[218:219], v[216:217]
	v_cvt_pk_bf16_f32 v227, v218, v219
	v_mul_f32_e32 v216, v90, v214
	v_mul_f32_e32 v217, v91, v214
	v_exp_f32_e32 v216, v216
	v_exp_f32_e32 v217, v217
	v_pk_mul_f32 v[218:219], v[90:91], v[82:83]
	v_pk_add_f32 v[216:217], v[216:217], 1.0 op_sel_hi:[1,0]
	v_pk_mul_f32 v[218:219], v[218:219], v[220:221] op_sel_hi:[1,0]
	v_rcp_f32_e32 v216, v216
	v_rcp_f32_e32 v217, v217
	s_nop 0
	v_pk_mul_f32 v[218:219], v[218:219], v[216:217]
	v_cvt_pk_bf16_f32 v228, v218, v219
	v_mul_f32_e32 v216, v92, v214
	v_mul_f32_e32 v217, v93, v214
	v_exp_f32_e32 v216, v216
	v_exp_f32_e32 v217, v217
	v_pk_mul_f32 v[218:219], v[92:93], v[84:85]
	v_pk_add_f32 v[216:217], v[216:217], 1.0 op_sel_hi:[1,0]
	v_pk_mul_f32 v[218:219], v[218:219], v[220:221] op_sel_hi:[1,0]
	v_rcp_f32_e32 v216, v216
	v_rcp_f32_e32 v217, v217
	s_nop 0
	v_pk_mul_f32 v[218:219], v[218:219], v[216:217]
	v_cvt_pk_bf16_f32 v229, v218, v219
	v_add_u32_e32 v222, 32, v148
	v_mad_i64_i32 v[224:225], s[18:19], v222, s41, v[212:213]
	v_lshl_add_u64 v[224:225], v[224:225], 0, v[210:211]
	global_store_dwordx4 v[224:225], v[226:229], off
	s_waitcnt lgkmcnt(4)
; __device__ __forceinline__ unsigned cvt_pk_bf16(float lo, float hi) { unsigned r; asm volatile("v_cvt_pk_bf16_f32 %0, %1, %2" : "=v"(r) : "v"(lo), "v"(hi)); return r; }
;     __device__ __forceinline__ void operator()(const f32x4 (&acc)[2][2][4][2], const Unit& u, int wr, int wc, int fr, int fq) const {
;         const int row0 = u.pm * BM + u.roff + wr * 64 + fr, col0 = u.pn * HALF + wc * 32 + 8 * fq;
; #pragma unroll
;         for (int ai = 0; ai < NAI; ++ai)
; #pragma unroll
;             for (int m = 0; m < 4; ++m) {
;                 const int row = row0 + ai * HALF + m * 16; const float ri = tab[u.par * 256 + ai * HALF + wr * 64 + m * 16 + fr];
;                 const f32x4 g0 = acc[ai][0][m][0] * ri, g1 = acc[ai][0][m][1] * ri, u0 = acc[ai][1][m][0] * ri, u1 = acc[ai][1][m][1] * ri;
;                 u32x4 w;
;                 w.x = pg8::cvt_pk_bf16(silu_mul(g0[0], u0[0]), silu_mul(g0[1], u0[1])); w.y = pg8::cvt_pk_bf16(silu_mul(g0[2], u0[2]), silu_mul(g0[3], u0[3]));
;                 w.z = pg8::cvt_pk_bf16(silu_mul(g1[0], u1[0]), silu_mul(g1[1], u1[1])); w.w = pg8::cvt_pk_bf16(silu_mul(g1[2], u1[2]), silu_mul(g1[3], u1[3]));
;                 *(u32x4*)(O + (size_t)row * DFF + col0) = w;
;                 if (m & 1) asm volatile("" ::: "memory");
;             }
	v_mul_f32_e32 v214, 0xbfb8aa3b, v205
	v_mul_f32_e32 v220, v205, v205
	v_mul_f32_e32 v216, v76, v214
	v_mul_f32_e32 v217, v77, v214
	v_exp_f32_e32 v216, v216
	v_exp_f32_e32 v217, v217
	v_pk_mul_f32 v[218:219], v[76:77], v[68:69]
	v_pk_add_f32 v[216:217], v[216:217], 1.0 op_sel_hi:[1,0]
	v_pk_mul_f32 v[218:219], v[218:219], v[220:221] op_sel_hi:[1,0]
	v_rcp_f32_e32 v216, v216
	v_rcp_f32_e32 v217, v217
	s_nop 0
	v_pk_mul_f32 v[218:219], v[218:219], v[216:217]
	v_cvt_pk_bf16_f32 v226, v218, v219
	v_mul_f32_e32 v216, v78, v214
	v_mul_f32_e32 v217, v79, v214
	v_exp_f32_e32 v216, v216
	v_exp_f32_e32 v217, v217
	v_pk_mul_f32 v[218:219], v[78:79], v[70:71]
	v_pk_add_f32 v[216:217], v[216:217], 1.0 op_sel_hi:[1,0]
	v_pk_mul_f32 v[218:219], v[218:219], v[220:221] op_sel_hi:[1,0]
	v_rcp_f32_e32 v216, v216
	v_rcp_f32_e32 v217, v217
	s_nop 0
	v_pk_mul_f32 v[218:219], v[218:219], v[216:217]
	v_cvt_pk_bf16_f32 v227, v218, v219
	v_mul_f32_e32 v216, v72, v214
	v_mul_f32_e32 v217, v73, v214
	v_exp_f32_e32 v216, v216
	v_exp_f32_e32 v217, v217
	v_pk_mul_f32 v[218:219], v[72:73], v[64:65]
	v_pk_add_f32 v[216:217], v[216:217], 1.0 op_sel_hi:[1,0]
	v_pk_mul_f32 v[218:219], v[218:219], v[220:221] op_sel_hi:[1,0]
	v_rcp_f32_e32 v216, v216
	v_rcp_f32_e32 v217, v217
	s_nop 0
	v_pk_mul_f32 v[218:219], v[218:219], v[216:217]
	v_cvt_pk_bf16_f32 v228, v218, v219
	v_mul_f32_e32 v216, v74, v214
	v_mul_f32_e32 v217, v75, v214
	v_exp_f32_e32 v216, v216
	v_exp_f32_e32 v217, v217
	v_pk_mul_f32 v[218:219], v[74:75], v[66:67]
	v_pk_add_f32 v[216:217], v[216:217], 1.0 op_sel_hi:[1,0]
	v_pk_mul_f32 v[218:219], v[218:219], v[220:221] op_sel_hi:[1,0]
	v_rcp_f32_e32 v216, v216
	v_rcp_f32_e32 v217, v217
	s_nop 0
	v_pk_mul_f32 v[218:219], v[218:219], v[216:217]
	v_cvt_pk_bf16_f32 v229, v218, v219
	v_add_u32_e32 v222, 48, v148
	v_mad_i64_i32 v[224:225], s[18:19], v222, s41, v[212:213]
	v_lshl_add_u64 v[224:225], v[224:225], 0, v[210:211]
	global_store_dwordx4 v[224:225], v[226:229], off
	s_waitcnt lgkmcnt(3)
	v_mul_f32_e32 v214, 0xbfb8aa3b, v206
	v_mul_f32_e32 v220, v206, v206
	v_mul_f32_e32 v216, v60, v214
	v_mul_f32_e32 v217, v61, v214
	v_exp_f32_e32 v216, v216
	v_exp_f32_e32 v217, v217
	v_pk_mul_f32 v[218:219], v[60:61], v[52:53]
	v_pk_add_f32 v[216:217], v[216:217], 1.0 op_sel_hi:[1,0]
	v_pk_mul_f32 v[218:219], v[218:219], v[220:221] op_sel_hi:[1,0]
	v_rcp_f32_e32 v216, v216
	v_rcp_f32_e32 v217, v217
	s_nop 0
	v_pk_mul_f32 v[218:219], v[218:219], v[216:217]
	v_cvt_pk_bf16_f32 v226, v218, v219
	v_mul_f32_e32 v216, v62, v214
	v_mul_f32_e32 v217, v63, v214
	v_exp_f32_e32 v216, v216
	v_exp_f32_e32 v217, v217
	v_pk_mul_f32 v[218:219], v[62:63], v[54:55]
	v_pk_add_f32 v[216:217], v[216:217], 1.0 op_sel_hi:[1,0]
	v_pk_mul_f32 v[218:219], v[218:219], v[220:221] op_sel_hi:[1,0]
	v_rcp_f32_e32 v216, v216
	v_rcp_f32_e32 v217, v217
	s_nop 0
	v_pk_mul_f32 v[218:219], v[218:219], v[216:217]
	v_cvt_pk_bf16_f32 v227, v218, v219
	v_mul_f32_e32 v216, v56, v214
	v_mul_f32_e32 v217, v57, v214
	v_exp_f32_e32 v216, v216
	v_exp_f32_e32 v217, v217
	v_pk_mul_f32 v[218:219], v[56:57], v[48:49]
	v_pk_add_f32 v[216:217], v[216:217], 1.0 op_sel_hi:[1,0]
	v_pk_mul_f32 v[218:219], v[218:219], v[220:221] op_sel_hi:[1,0]
	v_rcp_f32_e32 v216, v216
	v_rcp_f32_e32 v217, v217
	s_nop 0
	v_pk_mul_f32 v[218:219], v[218:219], v[216:217]
	v_cvt_pk_bf16_f32 v228, v218, v219
	v_mul_f32_e32 v216, v58, v214
	v_mul_f32_e32 v217, v59, v214
	v_exp_f32_e32 v216, v216
	v_exp_f32_e32 v217, v217
	v_pk_mul_f32 v[218:219], v[58:59], v[50:51]
	v_pk_add_f32 v[216:217], v[216:217], 1.0 op_sel_hi:[1,0]
	v_pk_mul_f32 v[218:219], v[218:219], v[220:221] op_sel_hi:[1,0]
	v_rcp_f32_e32 v216, v216
	v_rcp_f32_e32 v217, v217
	s_nop 0
	v_pk_mul_f32 v[218:219], v[218:219], v[216:217]
	v_cvt_pk_bf16_f32 v229, v218, v219
	v_add_u32_e32 v222, 0x80, v148
	v_mad_i64_i32 v[224:225], s[18:19], v222, s41, v[212:213]
	v_lshl_add_u64 v[224:225], v[224:225], 0, v[210:211]
	global_store_dwordx4 v[224:225], v[226:229], off
	s_waitcnt lgkmcnt(2)
	v_mul_f32_e32 v214, 0xbfb8aa3b, v207
	v_mul_f32_e32 v220, v207, v207
	v_mul_f32_e32 v216, v44, v214
	v_mul_f32_e32 v217, v45, v214
	v_exp_f32_e32 v216, v216
	v_exp_f32_e32 v217, v217
	v_pk_mul_f32 v[218:219], v[44:45], v[36:37]
	v_pk_add_f32 v[216:217], v[216:217], 1.0 op_sel_hi:[1,0]
	v_pk_mul_f32 v[218:219], v[218:219], v[220:221] op_sel_hi:[1,0]
	v_rcp_f32_e32 v216, v216
	v_rcp_f32_e32 v217, v217
	s_nop 0
	v_pk_mul_f32 v[218:219], v[218:219], v[216:217]
	v_cvt_pk_bf16_f32 v226, v218, v219
	v_mul_f32_e32 v216, v46, v214
	v_mul_f32_e32 v217, v47, v214
	v_exp_f32_e32 v216, v216
	v_exp_f32_e32 v217, v217
	v_pk_mul_f32 v[218:219], v[46:47], v[38:39]
	v_pk_add_f32 v[216:217], v[216:217], 1.0 op_sel_hi:[1,0]
	v_pk_mul_f32 v[218:219], v[218:219], v[220:221] op_sel_hi:[1,0]
	v_rcp_f32_e32 v216, v216
	v_rcp_f32_e32 v217, v217
	s_nop 0
	v_pk_mul_f32 v[218:219], v[218:219], v[216:217]
	v_cvt_pk_bf16_f32 v227, v218, v219
	v_mul_f32_e32 v216, v40, v214
	v_mul_f32_e32 v217, v41, v214
	v_exp_f32_e32 v216, v216
	v_exp_f32_e32 v217, v217
	v_pk_mul_f32 v[218:219], v[40:41], v[32:33]
	v_pk_add_f32 v[216:217], v[216:217], 1.0 op_sel_hi:[1,0]
	v_pk_mul_f32 v[218:219], v[218:219], v[220:221] op_sel_hi:[1,0]
	v_rcp_f32_e32 v216, v216
	v_rcp_f32_e32 v217, v217
	s_nop 0
	v_pk_mul_f32 v[218:219], v[218:219], v[216:217]
	v_cvt_pk_bf16_f32 v228, v218, v219
	v_mul_f32_e32 v216, v42, v214
	v_mul_f32_e32 v217, v43, v214
	v_exp_f32_e32 v216, v216
	v_exp_f32_e32 v217, v217
	v_pk_mul_f32 v[218:219], v[42:43], v[34:35]
	v_pk_add_f32 v[216:217], v[216:217], 1.0 op_sel_hi:[1,0]
	v_pk_mul_f32 v[218:219], v[218:219], v[220:221] op_sel_hi:[1,0]
	v_rcp_f32_e32 v216, v216
	v_rcp_f32_e32 v217, v217
	s_nop 0
	v_pk_mul_f32 v[218:219], v[218:219], v[216:217]
	v_cvt_pk_bf16_f32 v229, v218, v219
	v_add_u32_e32 v222, 0x90, v148
	v_mad_i64_i32 v[224:225], s[18:19], v222, s41, v[212:213]
	v_lshl_add_u64 v[224:225], v[224:225], 0, v[210:211]
	global_store_dwordx4 v[224:225], v[226:229], off
	s_waitcnt lgkmcnt(1)
; __device__ __forceinline__ unsigned cvt_pk_bf16(float lo, float hi) { unsigned r; asm volatile("v_cvt_pk_bf16_f32 %0, %1, %2" : "=v"(r) : "v"(lo), "v"(hi)); return r; }
; #define PG8_WAIT_V(n) asm volatile("s_waitcnt vmcnt(" #n ")" ::: "memory")
; #define PG8_BAR __builtin_amdgcn_s_barrier()
; template <class Epi, class Sched, bool ALIGN_EPI = false, bool SP2 = false, bool HALFM = false>
; __device__ __forceinline__ void gemm_phase(PG8_LAS unsigned char* lds, const Gemm g, const Sched& S, const Epi& E) {
;     ...
;         if constexpr (ALIGN_EPI) { if (wr == 1) PG8_BAR; }
;     }
;     PG8_WAIT_V(0);
;     if constexpr (!ALIGN_EPI) { if (wr == 0) PG8_BAR; }
;     PG8_BAR;
;     __device__ __forceinline__ void operator()(const f32x4 (&acc)[2][2][4][2], const Unit& u, int wr, int wc, int fr, int fq) const {
;         const int row0 = u.pm * BM + u.roff + wr * 64 + fr, col0 = u.pn * HALF + wc * 32 + 8 * fq;
; #pragma unroll
;         for (int ai = 0; ai < NAI; ++ai)
; #pragma unroll
;             for (int m = 0; m < 4; ++m) {
;                 const int row = row0 + ai * HALF + m * 16; const float ri = tab[u.par * 256 + ai * HALF + wr * 64 + m * 16 + fr];
;                 const f32x4 g0 = acc[ai][0][m][0] * ri, g1 = acc[ai][0][m][1] * ri, u0 = acc[ai][1][m][0] * ri, u1 = acc[ai][1][m][1] * ri;
;                 u32x4 w;
;                 w.x = pg8::cvt_pk_bf16(silu_mul(g0[0], u0[0]), silu_mul(g0[1], u0[1])); w.y = pg8::cvt_pk_bf16(silu_mul(g0[2], u0[2]), silu_mul(g0[3], u0[3]));
;                 w.z = pg8::cvt_pk_bf16(silu_mul(g1[0], u1[0]), silu_mul(g1[1], u1[1])); w.w = pg8::cvt_pk_bf16(silu_mul(g1[2], u1[2]), silu_mul(g1[3], u1[3]));
;                 *(u32x4*)(O + (size_t)row * DFF + col0) = w;
;                 if (m & 1) asm volatile("" ::: "memory");
;             }
	v_mul_f32_e32 v214, 0xbfb8aa3b, v208
	v_mul_f32_e32 v220, v208, v208
	v_mul_f32_e32 v216, v28, v214
	v_mul_f32_e32 v217, v29, v214
	v_exp_f32_e32 v216, v216
	v_exp_f32_e32 v217, v217
	v_pk_mul_f32 v[218:219], v[28:29], v[20:21]
	v_pk_add_f32 v[216:217], v[216:217], 1.0 op_sel_hi:[1,0]
	v_pk_mul_f32 v[218:219], v[218:219], v[220:221] op_sel_hi:[1,0]
	v_rcp_f32_e32 v216, v216
	v_rcp_f32_e32 v217, v217
	s_nop 0
	v_pk_mul_f32 v[218:219], v[218:219], v[216:217]
	v_cvt_pk_bf16_f32 v226, v218, v219
	v_mul_f32_e32 v216, v30, v214
	v_mul_f32_e32 v217, v31, v214
	v_exp_f32_e32 v216, v216
	v_exp_f32_e32 v217, v217
	v_pk_mul_f32 v[218:219], v[30:31], v[22:23]
	v_pk_add_f32 v[216:217], v[216:217], 1.0 op_sel_hi:[1,0]
	v_pk_mul_f32 v[218:219], v[218:219], v[220:221] op_sel_hi:[1,0]
	v_rcp_f32_e32 v216, v216
	v_rcp_f32_e32 v217, v217
	s_nop 0
	v_pk_mul_f32 v[218:219], v[218:219], v[216:217]
	v_cvt_pk_bf16_f32 v227, v218, v219
	v_mul_f32_e32 v216, v24, v214
	v_mul_f32_e32 v217, v25, v214
	v_exp_f32_e32 v216, v216
	v_exp_f32_e32 v217, v217
	v_pk_mul_f32 v[218:219], v[24:25], v[16:17]
	v_pk_add_f32 v[216:217], v[216:217], 1.0 op_sel_hi:[1,0]
	v_pk_mul_f32 v[218:219], v[218:219], v[220:221] op_sel_hi:[1,0]
	v_rcp_f32_e32 v216, v216
	v_rcp_f32_e32 v217, v217
	s_nop 0
	v_pk_mul_f32 v[218:219], v[218:219], v[216:217]
	v_cvt_pk_bf16_f32 v228, v218, v219
	v_mul_f32_e32 v216, v26, v214
	v_mul_f32_e32 v217, v27, v214
	v_exp_f32_e32 v216, v216
	v_exp_f32_e32 v217, v217
	v_pk_mul_f32 v[218:219], v[26:27], v[18:19]
	v_pk_add_f32 v[216:217], v[216:217], 1.0 op_sel_hi:[1,0]
	v_pk_mul_f32 v[218:219], v[218:219], v[220:221] op_sel_hi:[1,0]
	v_rcp_f32_e32 v216, v216
	v_rcp_f32_e32 v217, v217
	s_nop 0
	v_pk_mul_f32 v[218:219], v[218:219], v[216:217]
	v_cvt_pk_bf16_f32 v229, v218, v219
	v_add_u32_e32 v222, 0xa0, v148
	v_mad_i64_i32 v[224:225], s[18:19], v222, s41, v[212:213]
	v_lshl_add_u64 v[224:225], v[224:225], 0, v[210:211]
	global_store_dwordx4 v[224:225], v[226:229], off
	s_waitcnt lgkmcnt(0)
	v_mul_f32_e32 v214, 0xbfb8aa3b, v209
	v_mul_f32_e32 v220, v209, v209
	v_mul_f32_e32 v216, v12, v214
	v_mul_f32_e32 v217, v13, v214
	v_exp_f32_e32 v216, v216
	v_exp_f32_e32 v217, v217
	v_pk_mul_f32 v[218:219], v[12:13], v[4:5]
	v_pk_add_f32 v[216:217], v[216:217], 1.0 op_sel_hi:[1,0]
	v_pk_mul_f32 v[218:219], v[218:219], v[220:221] op_sel_hi:[1,0]
	v_rcp_f32_e32 v216, v216
	v_rcp_f32_e32 v217, v217
	s_nop 0
	v_pk_mul_f32 v[218:219], v[218:219], v[216:217]
	v_cvt_pk_bf16_f32 v226, v218, v219
	v_mul_f32_e32 v216, v14, v214
	v_mul_f32_e32 v217, v15, v214
	v_exp_f32_e32 v216, v216
	v_exp_f32_e32 v217, v217
	v_pk_mul_f32 v[218:219], v[14:15], v[6:7]
	v_pk_add_f32 v[216:217], v[216:217], 1.0 op_sel_hi:[1,0]
	v_pk_mul_f32 v[218:219], v[218:219], v[220:221] op_sel_hi:[1,0]
	v_rcp_f32_e32 v216, v216
	v_rcp_f32_e32 v217, v217
	s_nop 0
	v_pk_mul_f32 v[218:219], v[218:219], v[216:217]
	v_cvt_pk_bf16_f32 v227, v218, v219
	v_mul_f32_e32 v216, v8, v214
	v_mul_f32_e32 v217, v9, v214
	v_exp_f32_e32 v216, v216
	v_exp_f32_e32 v217, v217
	v_pk_mul_f32 v[218:219], v[8:9], v[0:1]
	v_pk_add_f32 v[216:217], v[216:217], 1.0 op_sel_hi:[1,0]
	v_pk_mul_f32 v[218:219], v[218:219], v[220:221] op_sel_hi:[1,0]
	v_rcp_f32_e32 v216, v216
	v_rcp_f32_e32 v217, v217
	s_nop 0
	v_pk_mul_f32 v[218:219], v[218:219], v[216:217]
	v_cvt_pk_bf16_f32 v228, v218, v219
	v_mul_f32_e32 v216, v10, v214
	v_mul_f32_e32 v217, v11, v214
	v_exp_f32_e32 v216, v216
	v_exp_f32_e32 v217, v217
	v_pk_mul_f32 v[218:219], v[10:11], v[2:3]
	v_pk_add_f32 v[216:217], v[216:217], 1.0 op_sel_hi:[1,0]
	v_pk_mul_f32 v[218:219], v[218:219], v[220:221] op_sel_hi:[1,0]
	v_rcp_f32_e32 v216, v216
	v_rcp_f32_e32 v217, v217
	s_nop 0
	v_pk_mul_f32 v[218:219], v[218:219], v[216:217]
	v_cvt_pk_bf16_f32 v229, v218, v219
	v_add_u32_e32 v222, 0xb0, v148
	v_mad_i64_i32 v[224:225], s[18:19], v222, s41, v[212:213]
	v_lshl_add_u64 v[224:225], v[224:225], 0, v[210:211]
	global_store_dwordx4 v[224:225], v[226:229], off
	s_andn2_b64 vcc, exec, s[16:17]
	s_mov_b64 s[18:19], -1
	s_cbranch_vccnz .LBB0_174
	s_andn2_b64 vcc, exec, s[0:1]
	s_cbranch_vccnz .LBB0_173
	s_barrier
	s_branch .LBB0_173
.LBB0_188:
	s_waitcnt vmcnt(0)
.LBB0_189:
	v_readlane_b32 s0, v254, 51
	v_readlane_b32 s1, v254, 52
	s_andn2_b64 vcc, exec, s[0:1]
	s_nop 0
	v_cndmask_b32_e64 v0, 0, 1, s[0:1]
	v_cmp_ne_u32_e64 s[4:5], 1, v0
	s_mov_b64 s[0:1], -1
	s_cbranch_vccnz .LBB0_207
	s_waitcnt vmcnt(0)
	s_waitcnt vmcnt(0)
	s_barrier
	s_mov_b64 s[0:1], exec
	v_readlane_b32 s8, v252, 3
	v_readlane_b32 s9, v252, 4
	s_and_b64 s[8:9], s[0:1], s[8:9]
	s_mov_b64 exec, s[8:9]
	s_cbranch_execz .LBB0_206
	v_readlane_b32 s8, v252, 8
	v_readlane_b32 s9, v252, 9
	s_waitcnt vmcnt(0) expcnt(0) lgkmcnt(0)
	s_mov_b32 s24, 1
	v_mov_b64_e32 v[0:1], s[8:9]
	buffer_inv sc1
	global_atomic_add v2, v[0:1], v250, off sc0
	s_waitcnt vmcnt(0)
	s_mov_b64 s[8:9], 0
	v_and_b32_e32 v0, 0xffffffe0, v2
	v_add_u32_e32 v0, 32, v0
	s_branch .LBB0_194

; #define PG8_WAIT_V(n) asm volatile("s_waitcnt vmcnt(" #n ")" ::: "memory")
; #define PG8_BAR __builtin_amdgcn_s_barrier()
; __device__ __forceinline__ unsigned xb_ld(unsigned* p)              { return __hip_atomic_load(p, __ATOMIC_RELAXED, __HIP_MEMORY_SCOPE_AGENT); }
; template <class Epi, class Sched, bool ALIGN_EPI = false, bool SP2 = false, bool HALFM = false>
; __device__ __forceinline__ void gemm_phase(PG8_LAS unsigned char* lds, const Gemm g, const Sched& S, const Epi& E) {
;     ...
;     PG8_WAIT_V(0);
;     if constexpr (!ALIGN_EPI) { if (wr == 0) PG8_BAR; }
;     PG8_BAR;
; __device__ __forceinline__ void local_barrier(unsigned* ctl, unsigned x) {
;     asm volatile("s_waitcnt vmcnt(0)" ::: "memory");
;     __syncthreads();
;     if (threadIdx.x == 0) {
;         __builtin_amdgcn_s_waitcnt(0);
;         unsigned* cw = &ctl[XL_CNT(x)];
;         const unsigned old = l2_fetch_add(cw, 1u), target = (old / 32u + 1u) * 32u;
;         unsigned sp = 0;
;         while (l2_fetch_add(cw, 0u) < target) {
;             __builtin_amdgcn_s_sleep(1);
;             if ((++sp & 255u) == 0u) { if (xb_ld(&ctl[XB_TMO])) break; if (sp > XB_SPIN_CAP) { atomicAdd(&ctl[XB_TMO], 1u); break; } } }
;         __builtin_amdgcn_fence(__ATOMIC_ACQUIRE, "agent");
;         asm volatile("s_waitcnt vmcnt(0)" ::: "memory");
;     }
.LBB0_513:
	s_waitcnt vmcnt(0)
.LBB0_514:
	v_readlane_b32 s0, v254, 51
	v_readlane_b32 s1, v254, 52
	s_andn2_b64 vcc, exec, s[0:1]
	s_nop 0
	v_cndmask_b32_e64 v0, 0, 1, s[0:1]
	v_cmp_ne_u32_e64 s[4:5], 1, v0
	s_mov_b64 s[0:1], -1
	s_nop 0
	v_writelane_b32 v255, s4, 0
	s_nop 1
	v_writelane_b32 v255, s5, 1
	s_cbranch_vccnz .LBB0_532
	s_waitcnt vmcnt(0)
	s_waitcnt lgkmcnt(0)
	s_barrier
	s_mov_b64 s[0:1], exec
	v_readlane_b32 s4, v252, 3
	v_readlane_b32 s5, v252, 4
	s_and_b64 s[4:5], s[0:1], s[4:5]
	s_mov_b64 exec, s[4:5]
	s_cbranch_execz .LBB0_531
	v_readlane_b32 s4, v252, 8
	v_readlane_b32 s5, v252, 9
	s_waitcnt vmcnt(0) expcnt(0) lgkmcnt(0)
	s_mov_b32 s20, 1
	v_mov_b64_e32 v[0:1], s[4:5]
	buffer_inv sc1
	global_atomic_add v2, v[0:1], v250, off sc0
	s_waitcnt vmcnt(0)
	s_mov_b64 s[4:5], 0
	v_and_b32_e32 v0, 0xffffffe0, v2
	v_add_u32_e32 v0, 32, v0
	s_branch .LBB0_519

; #define PG8_WAIT_V(n) asm volatile("s_waitcnt vmcnt(" #n ")" ::: "memory")
; #define PG8_BAR __builtin_amdgcn_s_barrier()
; __device__ __forceinline__ unsigned xb_ld(unsigned* p)              { return __hip_atomic_load(p, __ATOMIC_RELAXED, __HIP_MEMORY_SCOPE_AGENT); }
; template <class Epi, class Sched, bool ALIGN_EPI = false, bool SP2 = false, bool HALFM = false>
; __device__ __forceinline__ void gemm_phase(PG8_LAS unsigned char* lds, const Gemm g, const Sched& S, const Epi& E) {
;     ...
;     PG8_WAIT_V(0);
;     if constexpr (!ALIGN_EPI) { if (wr == 0) PG8_BAR; }
;     PG8_BAR;
; __device__ __forceinline__ void local_barrier(unsigned* ctl, unsigned x) {
;     asm volatile("s_waitcnt vmcnt(0)" ::: "memory");
;     __syncthreads();
;     if (threadIdx.x == 0) {
;         __builtin_amdgcn_s_waitcnt(0);
;         unsigned* cw = &ctl[XL_CNT(x)];
;         const unsigned old = l2_fetch_add(cw, 1u), target = (old / 32u + 1u) * 32u;
;         unsigned sp = 0;
;         while (l2_fetch_add(cw, 0u) < target) {
;             __builtin_amdgcn_s_sleep(1);
;             if ((++sp & 255u) == 0u) { if (xb_ld(&ctl[XB_TMO])) break; if (sp > XB_SPIN_CAP) { atomicAdd(&ctl[XB_TMO], 1u); break; } } }
;         __builtin_amdgcn_fence(__ATOMIC_ACQUIRE, "agent");
;         asm volatile("s_waitcnt vmcnt(0)" ::: "memory");
;     }
.LBB0_1187:
	s_waitcnt vmcnt(0)
.LBB0_1188:
	v_readlane_b32 s0, v255, 0
	v_readlane_b32 s1, v255, 1
	s_and_b64 vcc, exec, s[0:1]
	s_mov_b64 s[0:1], -1
	s_cbranch_vccnz .LBB0_1206
	s_waitcnt vmcnt(0)
	s_waitcnt lgkmcnt(0)
	s_barrier
	s_mov_b64 s[0:1], exec
	v_readlane_b32 s4, v252, 3
	v_readlane_b32 s5, v252, 4
	s_and_b64 s[4:5], s[0:1], s[4:5]
	s_mov_b64 exec, s[4:5]
	s_cbranch_execz .LBB0_1205
	v_readlane_b32 s4, v252, 8
	v_readlane_b32 s5, v252, 9
	s_waitcnt vmcnt(0) expcnt(0) lgkmcnt(0)
	s_mov_b32 s20, 1
	v_mov_b64_e32 v[0:1], s[4:5]
	buffer_inv sc1
	global_atomic_add v2, v[0:1], v250, off sc0
	s_waitcnt vmcnt(0)
	s_mov_b64 s[4:5], 0
	v_and_b32_e32 v0, 0xffffffe0, v2
	v_add_u32_e32 v0, 32, v0
	s_branch .LBB0_1193
